# v38 + hand-scheduled masked attention tile loop (exp/causal-mask/cvt/sums interleaved in PV MFMA gaps)
# speedup vs baseline: 1.0088x; 1.0002x over previous
.LBB0_587:
	s_setprio 1
	s_bitcmp1_b32 s31, 0
	s_cselect_b32 s4, 0x4400, 0
	v_add_u32_e32 v209, s4, v224
	ds_read_b128 v[2:5], v209
	ds_read_b128 v[6:9], v209 offset:32
	s_mul_i32 s4, s6, 0x5000
	s_waitcnt lgkmcnt(1)
	v_mfma_f32_32x32x16_bf16 v[128:143], v[2:5], v[144:147], v[96:111]
	ds_read_b128 v[2:5], v209 offset:8704
	ds_read_b128 v[10:13], v209 offset:8736
	s_waitcnt lgkmcnt(1)
	v_mfma_f32_32x32x16_bf16 v[112:127], v[2:5], v[144:147], v[96:111]
	v_mfma_f32_32x32x16_bf16 v[128:143], v[6:9], v[148:151], v[128:143]
	ds_read_b128 v[2:5], v209 offset:64
	ds_read_b128 v[6:9], v209 offset:96
	s_waitcnt lgkmcnt(2)
	v_mfma_f32_32x32x16_bf16 v[112:127], v[10:13], v[148:151], v[112:127]
	s_waitcnt lgkmcnt(1)
	v_mfma_f32_32x32x16_bf16 v[128:143], v[2:5], v[152:155], v[128:143]
	ds_read_b128 v[2:5], v209 offset:8768
	ds_read_b128 v[10:13], v209 offset:8800
	v_add_u32_e32 v209, s4, v225
	s_waitcnt lgkmcnt(1)
	v_mfma_f32_32x32x16_bf16 v[112:127], v[2:5], v[152:155], v[112:127]
	v_mfma_f32_32x32x16_bf16 v[128:143], v[6:9], v[156:159], v[128:143]
	ds_read_b64_tr_b16 v[2:3], v209 offset:34816
	ds_read_b64_tr_b16 v[6:7], v209 offset:34880
	ds_read_b64_tr_b16 v[236:237], v209 offset:34944
	ds_read_b64_tr_b16 v[240:241], v209 offset:35008
	ds_read_b64_tr_b16 v[4:5], v209 offset:37376
	ds_read_b64_tr_b16 v[8:9], v209 offset:37440
	ds_read_b64_tr_b16 v[238:239], v209 offset:37504
	ds_read_b64_tr_b16 v[242:243], v209 offset:37568
	s_waitcnt lgkmcnt(8)
	v_mfma_f32_32x32x16_bf16 v[112:127], v[10:13], v[156:159], v[112:127]
	s_waitcnt lgkmcnt(3)
	v_mfma_f32_32x32x16_bf16 v[64:79], v[188:191], v[2:5], v[64:79]
	ds_read_b64_tr_b16 v[2:3], v209 offset:39936
	ds_read_b64_tr_b16 v[4:5], v209 offset:42496
	v_exp_f32_e32 v128, v128
	v_cmp_gt_i32_e64 s[40:41], 0, v0
	v_exp_f32_e32 v129, v129
	v_cmp_gt_i32_e64 s[42:43], 1, v0
	v_cndmask_b32_e64 v128, v128, 0, s[40:41]
	v_exp_f32_e32 v130, v130
	v_cndmask_b32_e64 v129, v129, 0, s[42:43]
	v_cmp_gt_i32_e64 s[44:45], 2, v0
	s_waitcnt lgkmcnt(4)
	v_mfma_f32_32x32x16_bf16 v[80:95], v[188:191], v[6:9], v[80:95]
	ds_read_b64_tr_b16 v[6:7], v209 offset:40000
	ds_read_b64_tr_b16 v[8:9], v209 offset:42560
	v_cndmask_b32_e64 v130, v130, 0, s[44:45]
	v_exp_f32_e32 v131, v131
	v_cmp_gt_i32_e64 s[46:47], 3, v0
	v_exp_f32_e32 v132, v132
	v_cmp_gt_i32_e64 s[48:49], 8, v0
	v_cndmask_b32_e64 v131, v131, 0, s[46:47]
	v_exp_f32_e32 v133, v133
	v_cndmask_b32_e64 v132, v132, 0, s[48:49]
	s_waitcnt lgkmcnt(5)
	v_mfma_f32_32x32x16_bf16 v[48:63], v[188:191], v[236:239], v[48:63]
	ds_read_b64_tr_b16 v[10:11], v209 offset:40064
	ds_read_b64_tr_b16 v[12:13], v209 offset:42624
	v_cmp_gt_i32_e64 s[50:51], 9, v0
	v_exp_f32_e32 v134, v134
	v_cmp_gt_i32_e64 s[52:53], 10, v0
	v_cndmask_b32_e64 v133, v133, 0, s[50:51]
	v_exp_f32_e32 v135, v135
	v_cndmask_b32_e64 v134, v134, 0, s[52:53]
	v_cmp_gt_i32_e64 s[54:55], 11, v0
	v_exp_f32_e32 v136, v136
	s_waitcnt lgkmcnt(6)
	v_mfma_f32_32x32x16_bf16 v[32:47], v[188:191], v[240:243], v[32:47]
	ds_read_b64_tr_b16 v[28:29], v209 offset:40128
	ds_read_b64_tr_b16 v[30:31], v209 offset:42688
	v_cndmask_b32_e64 v135, v135, 0, s[54:55]
	v_cmp_gt_i32_e64 s[40:41], 16, v0
	v_exp_f32_e32 v137, v137
	v_cmp_gt_i32_e64 s[42:43], 17, v0
	v_cndmask_b32_e64 v136, v136, 0, s[40:41]
	v_exp_f32_e32 v138, v138
	v_cndmask_b32_e64 v137, v137, 0, s[42:43]
	v_cmp_gt_i32_e64 s[44:45], 18, v0
	v_cmp_gt_i32_e64 s[46:47], 19, v0
	s_waitcnt lgkmcnt(6)
	v_mfma_f32_32x32x16_bf16 v[64:79], v[184:187], v[2:5], v[64:79]
	ds_read_b64_tr_b16 v[2:3], v209 offset:45056
	ds_read_b64_tr_b16 v[4:5], v209 offset:47616
	v_cndmask_b32_e64 v138, v138, 0, s[44:45]
	v_exp_f32_e32 v139, v139
	v_exp_f32_e32 v140, v140
	v_cndmask_b32_e64 v139, v139, 0, s[46:47]
	v_cmp_gt_i32_e64 s[48:49], 24, v0
	v_exp_f32_e32 v141, v141
	v_cmp_gt_i32_e64 s[50:51], 25, v0
	v_cndmask_b32_e64 v140, v140, 0, s[48:49]
	s_waitcnt lgkmcnt(6)
	v_mfma_f32_32x32x16_bf16 v[80:95], v[184:187], v[6:9], v[80:95]
	ds_read_b64_tr_b16 v[6:7], v209 offset:45120
	ds_read_b64_tr_b16 v[8:9], v209 offset:47680
	v_cndmask_b32_e64 v141, v141, 0, s[50:51]
	v_exp_f32_e32 v142, v142
	v_cmp_gt_i32_e64 s[52:53], 26, v0
	v_exp_f32_e32 v143, v143
	v_cmp_gt_i32_e64 s[54:55], 27, v0
	v_cndmask_b32_e64 v142, v142, 0, s[52:53]
	v_exp_f32_e32 v112, v112
	v_cndmask_b32_e64 v143, v143, 0, s[54:55]
	s_waitcnt lgkmcnt(6)
	v_mfma_f32_32x32x16_bf16 v[48:63], v[184:187], v[10:13], v[48:63]
	ds_read_b64_tr_b16 v[10:11], v209 offset:45184
	ds_read_b64_tr_b16 v[12:13], v209 offset:47744
	v_cmp_gt_i32_e64 s[40:41], 32, v0
	v_exp_f32_e32 v113, v113
	v_cmp_gt_i32_e64 s[42:43], 33, v0
	v_cndmask_b32_e64 v112, v112, 0, s[40:41]
	v_exp_f32_e32 v114, v114
	v_cndmask_b32_e64 v113, v113, 0, s[42:43]
	v_cmp_gt_i32_e64 s[44:45], 34, v0
	v_exp_f32_e32 v115, v115
	s_waitcnt lgkmcnt(6)
; #define A_LOAD(t) do { _Pragma("unroll") for (int j_ = 0; j_ < 2; ++j_) { kreg[j_] = *(const u32x4*)(kg + (size_t)(64 * (t) + 32 * j_) * NIN); vreg[j_] = *(const u32x4*)(kg + 512 + (size_t)(64 * (t) + 32 * j_) * NIN); } } while (0)
; #define A_STORE(kbi, vbi) do { _Pragma("unroll") for (int j_ = 0; j_ < 2; ++j_) { *(LAS u32x4*)(lds + A_K0 + (kbi) * KBUF + (skey + 32 * j_) * KSTR + sch * 16) = kreg[j_]; *(LAS u32x4*)(lds + A_V0 + (vbi) * VBUF + (skey + 32 * j_) * VSTR + sch * 16) = vreg[j_]; } } while (0)
; __device__ __forceinline__ void attn_phase(LAS unsigned char* lds, const AttnArgs& a, int tid_in) {
;     ...
;         for (; t < NT; ++t) {
;             A_PIPE(true, t, vp);
;             if (t + 1 < NT) A_STORE((t + 1) & 1, vn);
;             if (t + 2 < NT) A_LOAD(t + 2);
;             __syncthreads();
;             vp = (vp == 2) ? 0 : vp + 1; vn = (vn == 2) ? 0 : vn + 1;
;         }
	v_mfma_f32_32x32x16_bf16 v[32:47], v[184:187], v[28:31], v[32:47]
	ds_read_b64_tr_b16 v[28:29], v209 offset:45248
	ds_read_b64_tr_b16 v[30:31], v209 offset:47808
	v_cndmask_b32_e64 v114, v114, 0, s[44:45]
	v_cmp_gt_i32_e64 s[46:47], 35, v0
	v_exp_f32_e32 v116, v116
	v_cmp_gt_i32_e64 s[48:49], 40, v0
	v_cndmask_b32_e64 v115, v115, 0, s[46:47]
	v_exp_f32_e32 v117, v117
	v_cndmask_b32_e64 v116, v116, 0, s[48:49]
	v_cmp_gt_i32_e64 s[50:51], 41, v0
	v_cmp_gt_i32_e64 s[52:53], 42, v0
	s_waitcnt lgkmcnt(6)
	v_mfma_f32_32x32x16_bf16 v[64:79], v[180:183], v[2:5], v[64:79]
	ds_read_b64_tr_b16 v[2:3], v209 offset:50176
	ds_read_b64_tr_b16 v[4:5], v209 offset:52736
	v_cndmask_b32_e64 v117, v117, 0, s[50:51]
	v_exp_f32_e32 v118, v118
	v_exp_f32_e32 v119, v119
	v_cndmask_b32_e64 v118, v118, 0, s[52:53]
	v_cmp_gt_i32_e64 s[54:55], 43, v0
	v_exp_f32_e32 v120, v120
	v_cmp_gt_i32_e64 s[40:41], 48, v0
	v_cndmask_b32_e64 v119, v119, 0, s[54:55]
	s_waitcnt lgkmcnt(6)
	v_mfma_f32_32x32x16_bf16 v[80:95], v[180:183], v[6:9], v[80:95]
	ds_read_b64_tr_b16 v[6:7], v209 offset:50240
	ds_read_b64_tr_b16 v[8:9], v209 offset:52800
	v_cndmask_b32_e64 v120, v120, 0, s[40:41]
	v_exp_f32_e32 v121, v121
	v_cmp_gt_i32_e64 s[42:43], 49, v0
	v_exp_f32_e32 v122, v122
	v_cmp_gt_i32_e64 s[44:45], 50, v0
	v_cndmask_b32_e64 v121, v121, 0, s[42:43]
	v_exp_f32_e32 v123, v123
	v_cndmask_b32_e64 v122, v122, 0, s[44:45]
	s_waitcnt lgkmcnt(6)
	v_mfma_f32_32x32x16_bf16 v[48:63], v[180:183], v[10:13], v[48:63]
	ds_read_b64_tr_b16 v[10:11], v209 offset:50304
	ds_read_b64_tr_b16 v[12:13], v209 offset:52864
	v_cmp_gt_i32_e64 s[46:47], 51, v0
	v_exp_f32_e32 v124, v124
	v_cmp_gt_i32_e64 s[48:49], 56, v0
	v_cndmask_b32_e64 v123, v123, 0, s[46:47]
	v_exp_f32_e32 v125, v125
	v_cndmask_b32_e64 v124, v124, 0, s[48:49]
	v_cmp_gt_i32_e64 s[50:51], 57, v0
	v_exp_f32_e32 v126, v126
	s_waitcnt lgkmcnt(6)
	v_mfma_f32_32x32x16_bf16 v[32:47], v[180:183], v[28:31], v[32:47]
	ds_read_b64_tr_b16 v[28:29], v209 offset:50368
	ds_read_b64_tr_b16 v[30:31], v209 offset:52928
	v_cndmask_b32_e64 v125, v125, 0, s[50:51]
	v_cmp_gt_i32_e64 s[52:53], 58, v0
	v_exp_f32_e32 v127, v127
	v_cmp_gt_i32_e64 s[54:55], 59, v0
	v_cndmask_b32_e64 v126, v126, 0, s[52:53]
	v_cvt_pk_bf16_f32 v188, v128, v129
	v_cndmask_b32_e64 v127, v127, 0, s[54:55]
	v_cvt_pk_bf16_f32 v189, v130, v131
	v_cvt_pk_bf16_f32 v190, v132, v133
	v_cvt_pk_bf16_f32 v191, v134, v135
	s_waitcnt lgkmcnt(6)
	v_mfma_f32_32x32x16_bf16 v[64:79], v[176:179], v[2:5], v[64:79]
	v_cvt_pk_bf16_f32 v184, v136, v137
	v_cvt_pk_bf16_f32 v185, v138, v139
	v_cvt_pk_bf16_f32 v186, v140, v141
	v_cvt_pk_bf16_f32 v187, v142, v143
	v_cvt_pk_bf16_f32 v180, v112, v113
	v_cvt_pk_bf16_f32 v181, v114, v115
	v_cvt_pk_bf16_f32 v182, v116, v117
	v_cvt_pk_bf16_f32 v183, v118, v119
	v_add_f32_e32 v17, v128, v129
	v_add_f32_e32 v17, v17, v130
	v_add_f32_e32 v17, v17, v131
	s_waitcnt lgkmcnt(4)
	v_mfma_f32_32x32x16_bf16 v[80:95], v[176:179], v[6:9], v[80:95]
	v_add_f32_e32 v17, v17, v132
	v_add_f32_e32 v17, v17, v133
	v_add_f32_e32 v17, v17, v134
	v_add_f32_e32 v17, v17, v135
	v_add_f32_e32 v18, v136, v137
	v_add_f32_e32 v18, v18, v138
	v_add_f32_e32 v18, v18, v139
	v_add_f32_e32 v18, v18, v140
	v_add_f32_e32 v18, v18, v141
	v_add_f32_e32 v18, v18, v142
	v_add_f32_e32 v18, v18, v143
	s_waitcnt lgkmcnt(2)
	v_mfma_f32_32x32x16_bf16 v[48:63], v[176:179], v[10:13], v[48:63]
	v_add_f32_e32 v19, v112, v113
	v_add_f32_e32 v19, v19, v114
	v_add_f32_e32 v19, v19, v115
	v_add_f32_e32 v19, v19, v116
	v_add_f32_e32 v19, v19, v117
	v_add_f32_e32 v19, v19, v118
	v_add_f32_e32 v19, v19, v119
	v_add_f32_e32 v20, v120, v121
	v_add_f32_e32 v20, v20, v122
	v_add_f32_e32 v20, v20, v123
	v_add_f32_e32 v20, v20, v124
	s_waitcnt lgkmcnt(0)
	v_mfma_f32_32x32x16_bf16 v[32:47], v[176:179], v[28:31], v[32:47]
	v_cvt_pk_bf16_f32 v176, v120, v121
	v_cvt_pk_bf16_f32 v177, v122, v123
	v_cvt_pk_bf16_f32 v178, v124, v125
	v_cvt_pk_bf16_f32 v179, v126, v127
	v_add_f32_e32 v20, v20, v125
	v_add_f32_e32 v20, v20, v126
	v_add_f32_e32 v20, v20, v127
	v_add_f32_e32 v17, v17, v18
	v_add_f32_e32 v19, v19, v20
	v_add_f32_e32 v17, v17, v19
	v_add_f32_e32 v211, v211, v17
	s_setprio 0
	s_add_i32 s35, s31, -1
	s_cmp_ge_i32 s35, s27
	s_cbranch_scc1 .Lattn_m_nowr
	s_bitcmp1_b32 s35, 0
	s_cselect_b32 s5, 0x4400, 0
	s_mul_i32 s4, s34, 0x5000
	v_add3_u32 v4, v223, s5, v228
	v_add3_u32 v3, v223, s4, v229
	s_waitcnt vmcnt(3)
	ds_write_b128 v4, v[160:163]
	s_waitcnt vmcnt(2)
	ds_write_b128 v3, v[164:167] offset:34816
	s_waitcnt vmcnt(1)
	ds_write_b128 v4, v[168:171] offset:8704
	s_waitcnt vmcnt(0)
	ds_write_b128 v3, v[172:175] offset:45056

; #define A_LOAD(t) do { _Pragma("unroll") for (int j_ = 0; j_ < 2; ++j_) { kreg[j_] = *(const u32x4*)(kg + (size_t)(64 * (t) + 32 * j_) * NIN); vreg[j_] = *(const u32x4*)(kg + 512 + (size_t)(64 * (t) + 32 * j_) * NIN); } } while (0)
; #define A_STORE(kbi, vbi) do { _Pragma("unroll") for (int j_ = 0; j_ < 2; ++j_) { *(LAS u32x4*)(lds + A_K0 + (kbi) * KBUF + (skey + 32 * j_) * KSTR + sch * 16) = kreg[j_]; *(LAS u32x4*)(lds + A_V0 + (vbi) * VBUF + (skey + 32 * j_) * VSTR + sch * 16) = vreg[j_]; } } while (0)
; __device__ __forceinline__ void attn_phase(LAS unsigned char* lds, const AttnArgs& a, int tid_in) {
;     ...
;             vp = (vp == 2) ? 0 : vp + 1; vn = (vn == 2) ? 0 : vn + 1;
;         }
;         for (; t < NT; ++t) {
;             A_PIPE(true, t, vp);
;             if (t + 1 < NT) A_STORE((t + 1) & 1, vn);
;             if (t + 2 < NT) A_LOAD(t + 2);
;             __syncthreads();
;             vp = (vp == 2) ? 0 : vp + 1; vn = (vn == 2) ? 0 : vn + 1;
;         }
.Lattn_m_nold:
	s_add_i32 s4, s6, 1
	s_cmp_lg_u32 s6, 2
	s_cselect_b32 s6, s4, 0
	s_add_i32 s4, s34, 1
	s_cmp_lg_u32 s34, 2
	s_cselect_b32 s34, s4, 0
	s_add_i32 s30, s30, 64
	s_add_i32 s31, s31, 1
	v_subrev_u32_e32 v0, 64, v0
	s_cmp_lt_i32 s35, s27
	s_waitcnt lgkmcnt(0)
	s_barrier
	s_cbranch_scc1 .LBB0_587
	s_branch .LBB0_591
